# p-conversion loop: guarded 4-iteration batch (8 loads in flight, counted waits); x0: second load group issued before first wait
# baseline (speedup 1.0000x reference)
; __device__ __forceinline__ unsigned cvt_pk_bf16(float lo, float hi) { unsigned r; asm("v_cvt_pk_bf16_f32 %0, %1, %2" : "=v"(r) : "v"(lo), "v"(hi)); return r; }
; __device__ __forceinline__ int obid() { extern __shared__ __attribute__((aligned(16))) unsigned char shm_vb[]; return __builtin_amdgcn_readfirstlane(*(volatile LAS int*)((LAS unsigned char*)shm_vb + VB_OFF)); }
; __device__ __forceinline__ unsigned long long ss_fix(float s) { return (unsigned long long)(s * 16777216.f); }
; __device__ __forceinline__ void phase_x0(const float* __restrict__ x, bf16_t* __restrict__ xb, unsigned long long* __restrict__ ss, int rows) {
;     ...
;   for (int r = obid() * 8 + (tid >> 6); r < rows; r += nw) {
;     const float4* xr = (const float4*)(x + (size_t)r * DM);
;     float4 v[8]; float s = 0.f;
; #pragma unroll
;     for (int i = 0; i < 8; ++i) { v[i] = xr[lane + 64 * i]; s += v[i].x * v[i].x + v[i].y * v[i].y + v[i].z * v[i].z + v[i].w * v[i].w; }
;     s = wave_sum(s);
; #pragma unroll
;     for (int i = 0; i < 8; ++i) {
;       uint2 o; o.x = cvt_pk_bf16(v[i].x, v[i].y); o.y = cvt_pk_bf16(v[i].z, v[i].w);
;       *(uint2*)(xb + (size_t)r * DM + (lane + 64 * i) * 4) = o;
;     }
;     if (lane == 0) ss[r] = ss_fix(s);
.LBB0_88:
	s_waitcnt lgkmcnt(0)
	global_load_dwordx4 v[14:17], v[4:5], off
	global_load_dwordx4 v[18:21], v[4:5], off offset:1024
	global_load_dwordx4 v[22:25], v[4:5], off offset:2048
	global_load_dwordx4 v[26:29], v[4:5], off offset:3072
	v_add_co_u32_e64 v42, s[2:3], s77, v4
	s_nop 1
	v_addc_co_u32_e64 v43, s[2:3], 0, v5, s[2:3]
	global_load_dwordx4 v[30:33], v[42:43], off
	global_load_dwordx4 v[34:37], v[42:43], off offset:1024
	global_load_dwordx4 v[38:41], v[42:43], off offset:2048
	s_nop 0
	global_load_dwordx4 v[42:45], v[42:43], off offset:3072
	s_waitcnt vmcnt(4) lgkmcnt(0)
	v_mul_f32_e32 v13, v15, v15
	v_mul_f32_e32 v46, v19, v19
	v_mul_f32_e32 v47, v23, v23
	v_fmac_f32_e32 v13, v14, v14
	v_fmac_f32_e32 v46, v18, v18
	v_mul_f32_e32 v48, v27, v27
	v_fmac_f32_e32 v47, v22, v22
	v_fmac_f32_e32 v13, v16, v16
	v_fmac_f32_e32 v46, v20, v20
	v_fmac_f32_e32 v48, v26, v26
	v_fmac_f32_e32 v47, v24, v24
	v_fmac_f32_e32 v13, v17, v17
	v_fmac_f32_e32 v46, v21, v21
	v_fmac_f32_e32 v48, v28, v28
	v_fmac_f32_e32 v47, v25, v25
	v_add_f32_e32 v13, v13, v46
	v_fmac_f32_e32 v48, v29, v29
	v_add_f32_e32 v13, v13, v47
	v_add_f32_e32 v13, v13, v48
	v_cvt_pk_bf16_f32 v14, v14, v15
	v_cvt_pk_bf16_f32 v15, v16, v17
	v_cvt_pk_bf16_f32 v16, v18, v19
	v_cvt_pk_bf16_f32 v18, v22, v23
	v_cvt_pk_bf16_f32 v17, v20, v21
	v_cvt_pk_bf16_f32 v19, v24, v25
	global_store_dwordx2 v[2:3], v[14:15], off
	global_store_dwordx2 v[2:3], v[16:17], off offset:512
	global_store_dwordx2 v[2:3], v[18:19], off offset:1024
	s_waitcnt vmcnt(0) lgkmcnt(0)
	v_cvt_pk_bf16_f32 v14, v30, v31
	v_mul_f32_e32 v49, v31, v31
	v_mul_f32_e32 v50, v35, v35
	v_fmac_f32_e32 v49, v30, v30
	v_mul_f32_e32 v51, v39, v39
	v_fmac_f32_e32 v50, v34, v34
	v_fmac_f32_e32 v49, v32, v32
	v_mul_f32_e32 v52, v43, v43
	v_fmac_f32_e32 v51, v38, v38
	v_fmac_f32_e32 v50, v36, v36
	v_fmac_f32_e32 v49, v33, v33
	v_fmac_f32_e32 v52, v42, v42
	v_fmac_f32_e32 v51, v40, v40
	v_fmac_f32_e32 v50, v37, v37
	v_add_f32_e32 v13, v13, v49
	v_fmac_f32_e32 v52, v44, v44
	v_fmac_f32_e32 v51, v41, v41
	v_add_f32_e32 v13, v13, v50
	v_fmac_f32_e32 v52, v45, v45
	v_add_f32_e32 v13, v13, v51
	v_add_f32_e32 v13, v13, v52
	ds_bpermute_b32 v46, v7, v13
	v_cvt_pk_bf16_f32 v15, v32, v33
	v_cvt_pk_bf16_f32 v20, v26, v27
	v_cvt_pk_bf16_f32 v21, v28, v29
	global_store_dwordx2 v[2:3], v[20:21], off offset:1536
	s_waitcnt lgkmcnt(0)
	v_add_f32_e32 v13, v13, v46
	ds_bpermute_b32 v46, v8, v13
	v_cvt_pk_bf16_f32 v16, v34, v35
	v_cvt_pk_bf16_f32 v18, v38, v39
	s_waitcnt lgkmcnt(0)
	v_add_f32_e32 v13, v13, v46
	ds_bpermute_b32 v22, v9, v13
	s_waitcnt lgkmcnt(0)
	v_add_f32_e32 v13, v13, v22
	ds_bpermute_b32 v17, v10, v13
	s_waitcnt lgkmcnt(0)
	v_add_f32_e32 v13, v13, v17
	ds_bpermute_b32 v19, v11, v13
	v_cvt_pk_bf16_f32 v17, v36, v37
	global_store_dwordx2 v[2:3], v[14:15], off offset:2048
	global_store_dwordx2 v[2:3], v[16:17], off offset:2560
	v_cvt_pk_bf16_f32 v16, v42, v43
	v_cvt_pk_bf16_f32 v17, v44, v45
	s_waitcnt lgkmcnt(0)
	v_add_f32_e32 v13, v13, v19
	ds_bpermute_b32 v14, v12, v13
	v_cvt_pk_bf16_f32 v19, v40, v41
	global_store_dwordx2 v[2:3], v[18:19], off offset:3072
	global_store_dwordx2 v[2:3], v[16:17], off offset:3584
	s_and_saveexec_b64 s[2:3], vcc
	s_cbranch_execz .LBB0_87
	s_waitcnt lgkmcnt(0)
	v_add_f32_e32 v13, v13, v14
	v_mul_f32_e32 v13, 0x4b800000, v13
	v_trunc_f32_e32 v13, v13
	v_mul_f32_e32 v14, 0x2f800000, v13
	v_floor_f32_e32 v15, v14
	v_fmac_f32_e32 v13, 0xcf800000, v15
	v_cvt_u32_f32_e32 v14, v13
	v_cvt_u32_f32_e32 v15, v15
	global_store_dwordx2 v[0:1], v[14:15], off
	s_branch .LBB0_87

; __device__ __forceinline__ unsigned cvt_pk_bf16(float lo, float hi) { unsigned r; asm("v_cvt_pk_bf16_f32 %0, %1, %2" : "=v"(r) : "v"(lo), "v"(hi)); return r; }
; __device__ __forceinline__ int otid() { int t = threadIdx.x; asm volatile("" : "+v"(t)); return t; }
; __device__ __forceinline__ int obid() { extern __shared__ __attribute__((aligned(16))) unsigned char shm_vb[]; return __builtin_amdgcn_readfirstlane(*(volatile LAS int*)((LAS unsigned char*)shm_vb + VB_OFF)); }
; __device__ __forceinline__ void phase_cvt(const float* __restrict__ src, int ld, int rows, int ncols, bf16_t* __restrict__ dst, const float* __restrict__ gain = nullptr) {
;   const size_t n8 = (size_t)rows * ncols / 8, gs = (size_t)gridDim.x * 512;
;   const int c8 = ncols / 8;
;   for (size_t i = (size_t)obid() * 512 + otid(); i < n8; i += gs) {
;     const size_t r = i / c8; const int c = (int)(i % c8) * 8;
;     const float* s = src + r * ld + c;
;     float4 v0 = *(const float4*)s, v1 = *(const float4*)(s + 4);
;     if (gain) { const float g = gain[r]; v0.x *= g; v0.y *= g; v0.z *= g; v0.w *= g; v1.x *= g; v1.y *= g; v1.z *= g; v1.w *= g; }
;     uint4 o; o.x = cvt_pk_bf16(v0.x, v0.y); o.y = cvt_pk_bf16(v0.z, v0.w); o.z = cvt_pk_bf16(v1.x, v1.y); o.w = cvt_pk_bf16(v1.z, v1.w);
;     *(uint4*)(dst + r * ncols + c) = o;
;   }
.LBB0_91:
	s_lshl_b64 s[0:1], s[88:89], 3
	v_readlane_b32 s2, v255, 0
	v_readlane_b32 s3, v255, 1
	s_add_u32 s0, s2, s0
	s_addc_u32 s1, s3, s1
	v_mov_b64_e32 v[0:1], s[0:1]
	global_load_dwordx2 v[4:5], v[0:1], off offset:16 sc0 sc1
	s_waitcnt vmcnt(0)
	v_mov_b64_e32 v[0:1], s[2:3]
	global_load_dwordx2 v[6:7], v[0:1], off offset:120 sc0 sc1
	s_waitcnt vmcnt(0)
	v_mov_b32_e32 v0, s74
	ds_read_b32 v0, v0
	v_mov_b32_e32 v2, v252
	s_mov_b64 s[2:3], 0x80000
	v_ashrrev_i32_e32 v3, 31, v2
	s_waitcnt lgkmcnt(0)
	v_readfirstlane_b32 s8, v0
	s_ashr_i32 s9, s8, 31
	s_lshl_b64 s[0:1], s[8:9], 9
	v_lshl_add_u64 v[0:1], s[0:1], 0, v[2:3]
	v_cmp_gt_u64_e32 vcc, s[2:3], v[0:1]
	v_readfirstlane_b32 s1, v5
	v_readfirstlane_b32 s4, v4
	v_readfirstlane_b32 s0, v7
	v_readfirstlane_b32 s6, v6
	s_and_saveexec_b64 s[2:3], vcc
	s_cbranch_execz .LBB0_94
	v_readlane_b32 s18, v255, 30
	v_readlane_b32 s19, v255, 31
	s_add_u32 s4, s4, s18
	s_addc_u32 s5, s1, s19
	s_add_u32 s6, s6, 0x13980000
	s_addc_u32 s7, s0, 0
	s_lshl_b64 s[0:1], s[8:9], 12
	v_lshl_add_u64 v[2:3], v[2:3], 3, s[0:1]
	s_mov_b64 s[8:9], 0
	s_cmp_eq_u32 s14, 0x20000
	s_cbranch_scc0 .LBB0_93
	s_cmp_eq_u32 s15, 0
	s_cbranch_scc0 .LBB0_93
	v_add_u32_e32 v49, s24, v2
	v_add_u32_e32 v50, s24, v49
	v_add_u32_e32 v51, s24, v50
	v_and_b32_e32 v48, 0x3ffff8, v2
	v_and_b32_e32 v49, 0x3ffff8, v49
	v_and_b32_e32 v50, 0x3ffff8, v50
	v_and_b32_e32 v51, 0x3ffff8, v51
	v_lshlrev_b32_e32 v52, 2, v48
	v_lshlrev_b32_e32 v53, 2, v49
	v_lshlrev_b32_e32 v54, 2, v50
	v_lshlrev_b32_e32 v55, 2, v51
	global_load_dwordx4 v[16:19], v52, s[4:5]
	global_load_dwordx4 v[20:23], v52, s[4:5] offset:16
	global_load_dwordx4 v[24:27], v53, s[4:5]
	global_load_dwordx4 v[28:31], v53, s[4:5] offset:16
	global_load_dwordx4 v[32:35], v54, s[4:5]
	global_load_dwordx4 v[36:39], v54, s[4:5] offset:16
	global_load_dwordx4 v[40:43], v55, s[4:5]
	global_load_dwordx4 v[44:47], v55, s[4:5] offset:16
	v_lshlrev_b32_e32 v48, 1, v48
	v_lshlrev_b32_e32 v49, 1, v49
	v_lshlrev_b32_e32 v50, 1, v50
	v_lshlrev_b32_e32 v51, 1, v51
	s_waitcnt vmcnt(6)
	v_cvt_pk_bf16_f32 v16, v16, v17
	v_cvt_pk_bf16_f32 v17, v18, v19
	v_cvt_pk_bf16_f32 v18, v20, v21
	v_cvt_pk_bf16_f32 v19, v22, v23
	global_store_dwordx4 v48, v[16:19], s[6:7]
	s_waitcnt vmcnt(5)
	v_cvt_pk_bf16_f32 v24, v24, v25
	v_cvt_pk_bf16_f32 v25, v26, v27
	v_cvt_pk_bf16_f32 v26, v28, v29
	v_cvt_pk_bf16_f32 v27, v30, v31
	global_store_dwordx4 v49, v[24:27], s[6:7]
	s_waitcnt vmcnt(4)
	v_cvt_pk_bf16_f32 v32, v32, v33
	v_cvt_pk_bf16_f32 v33, v34, v35
	v_cvt_pk_bf16_f32 v34, v36, v37
	v_cvt_pk_bf16_f32 v35, v38, v39
	global_store_dwordx4 v50, v[32:35], s[6:7]
	s_waitcnt vmcnt(3)
	v_cvt_pk_bf16_f32 v40, v40, v41
	v_cvt_pk_bf16_f32 v41, v42, v43
	v_cvt_pk_bf16_f32 v42, v44, v45
	v_cvt_pk_bf16_f32 v43, v46, v47
	global_store_dwordx4 v51, v[40:43], s[6:7]
	s_branch .LBB0_94
